# v68: transposing norm phase: per-row loop replaced by two straight-line passes of 4 rows per wave (loads in flight together, DPP/permlane reductions)
# baseline (speedup 1.0000x reference)
.LBB0_896:
	s_lshl_b32 s8, s7, 6
	v_readlane_b32 s9, v254, 63
	s_lshl_b32 s3, s9, 3
	s_add_i32 s16, s8, s3
	s_mov_b32 s17, 0
	s_sub_i32 s1, s8, 0x1800
	s_max_i32 s1, s1, 0
	s_lshr_b32 s1, s1, 11
	s_ashr_i32 s0, s80, 2
	s_and_b32 s6, s80, 3
	s_mul_i32 s3, s0, 3
	s_add_i32 s8, s3, s6
	v_readlane_b32 s10, v255, 14
	v_readlane_b32 s11, v255, 15
	s_load_dwordx2 s[12:13], s[10:11], 0x58
	s_add_i32 s3, s3, s1
	s_mul_i32 s3, s3, 0x9000
	s_mul_i32 s14, s6, 0x3000
	s_add_i32 s3, s3, s14
	s_add_i32 s3, s3, 0x100000
	v_readlane_b32 s18, v255, 7
	v_readlane_b32 s19, v255, 8
	s_add_u32 s18, s18, s3
	s_addc_u32 s19, s19, 0
	v_lshrrev_b32_e32 v200, 2, v18
	v_lshlrev_b32_e32 v201, 5, v200
	v_lshlrev_b32_e32 v202, 4, v200
	s_lshl_b32 s9, s9, 14
	v_add_u32_e32 v202, s9, v202
	s_lshl_b32 s8, s8, 12
	s_add_u32 s14, s18, 0x1000
	s_addc_u32 s15, s19, 0
	s_waitcnt lgkmcnt(0)
	s_add_u32 s12, s12, s8
	s_addc_u32 s13, s13, 0
	global_load_dwordx4 v[134:137], v201, s[12:13] offset:0
	global_load_dwordx4 v[150:153], v201, s[14:15] offset:0
	global_load_dwordx4 v[170:173], v201, s[18:19] offset:0
	global_load_dwordx4 v[138:141], v201, s[12:13] offset:16
	global_load_dwordx4 v[154:157], v201, s[14:15] offset:16
	global_load_dwordx4 v[174:177], v201, s[18:19] offset:16
	global_load_dwordx4 v[142:145], v201, s[12:13] offset:2048
	global_load_dwordx4 v[158:161], v201, s[14:15] offset:2048
	global_load_dwordx4 v[178:181], v201, s[18:19] offset:2048
	global_load_dwordx4 v[146:149], v201, s[12:13] offset:2064
	global_load_dwordx4 v[162:165], v201, s[14:15] offset:2064
	global_load_dwordx4 v[182:185], v201, s[18:19] offset:2064
	v_readlane_b32 s10, v255, 5
	v_readlane_b32 s11, v255, 6
	s_lshl_b64 s[12:13], s[16:17], 12
	s_add_u32 s10, s10, s12
	s_addc_u32 s11, s11, s13
	s_mov_b32 s3, 0x3a800000
	global_load_dwordx4 v[70:73], v201, s[10:11] offset:0
	global_load_dwordx4 v[74:77], v201, s[10:11] offset:16
	global_load_dwordx4 v[78:81], v201, s[10:11] offset:2048
	global_load_dwordx4 v[82:85], v201, s[10:11] offset:2064
	s_add_u32 s10, s10, 0x1000
	s_addc_u32 s11, s11, 0
	global_load_dwordx4 v[86:89], v201, s[10:11] offset:0
	global_load_dwordx4 v[90:93], v201, s[10:11] offset:16
	global_load_dwordx4 v[94:97], v201, s[10:11] offset:2048
	global_load_dwordx4 v[98:101], v201, s[10:11] offset:2064
	s_add_u32 s10, s10, 0x1000
	s_addc_u32 s11, s11, 0
	global_load_dwordx4 v[102:105], v201, s[10:11] offset:0
	global_load_dwordx4 v[106:109], v201, s[10:11] offset:16
	global_load_dwordx4 v[110:113], v201, s[10:11] offset:2048
	global_load_dwordx4 v[114:117], v201, s[10:11] offset:2064
	s_add_u32 s10, s10, 0x1000
	s_addc_u32 s11, s11, 0
	global_load_dwordx4 v[118:121], v201, s[10:11] offset:0
	global_load_dwordx4 v[122:125], v201, s[10:11] offset:16
	global_load_dwordx4 v[126:129], v201, s[10:11] offset:2048
	global_load_dwordx4 v[130:133], v201, s[10:11] offset:2064
	s_add_u32 s10, s10, 0x1000
	s_addc_u32 s11, s11, 0
	s_waitcnt vmcnt(16)
	v_add_f32_e32 v150, 1.0, v150
	v_add_f32_e32 v151, 1.0, v151
	v_add_f32_e32 v152, 1.0, v152
	v_add_f32_e32 v153, 1.0, v153
	v_add_f32_e32 v154, 1.0, v154
	v_add_f32_e32 v155, 1.0, v155
	v_add_f32_e32 v156, 1.0, v156
	v_add_f32_e32 v157, 1.0, v157
	v_add_f32_e32 v158, 1.0, v158
	v_add_f32_e32 v159, 1.0, v159
	v_add_f32_e32 v160, 1.0, v160
	v_add_f32_e32 v161, 1.0, v161
	v_add_f32_e32 v162, 1.0, v162
	v_add_f32_e32 v163, 1.0, v163
	v_add_f32_e32 v164, 1.0, v164
	v_add_f32_e32 v165, 1.0, v165
	v_mul_f32_e32 v150, v134, v150
	v_mul_f32_e32 v151, v135, v151
	v_mul_f32_e32 v152, v136, v152
	v_mul_f32_e32 v153, v137, v153
	v_mul_f32_e32 v154, v138, v154
	v_mul_f32_e32 v155, v139, v155
	v_mul_f32_e32 v156, v140, v156
	v_mul_f32_e32 v157, v141, v157
	v_mul_f32_e32 v158, v142, v158
	v_mul_f32_e32 v159, v143, v159
	v_mul_f32_e32 v160, v144, v160
	v_mul_f32_e32 v161, v145, v161
	v_mul_f32_e32 v162, v146, v162
	v_mul_f32_e32 v163, v147, v163
	v_mul_f32_e32 v164, v148, v164
	v_mul_f32_e32 v165, v149, v165
	s_waitcnt vmcnt(12)
	v_mul_f32_e32 v186, v70, v70
	v_fmac_f32_e32 v186, v71, v71
	v_fmac_f32_e32 v186, v72, v72
	v_fmac_f32_e32 v186, v73, v73
	v_fmac_f32_e32 v186, v74, v74
	v_fmac_f32_e32 v186, v75, v75
	v_fmac_f32_e32 v186, v76, v76
	v_fmac_f32_e32 v186, v77, v77
	v_fmac_f32_e32 v186, v78, v78
	v_fmac_f32_e32 v186, v79, v79
	v_fmac_f32_e32 v186, v80, v80
	v_fmac_f32_e32 v186, v81, v81
	v_fmac_f32_e32 v186, v82, v82
	v_fmac_f32_e32 v186, v83, v83
	v_fmac_f32_e32 v186, v84, v84
	v_fmac_f32_e32 v186, v85, v85
	s_waitcnt vmcnt(8)
	v_mul_f32_e32 v187, v86, v86
	v_fmac_f32_e32 v187, v87, v87
	v_fmac_f32_e32 v187, v88, v88
	v_fmac_f32_e32 v187, v89, v89
	v_fmac_f32_e32 v187, v90, v90
	v_fmac_f32_e32 v187, v91, v91
	v_fmac_f32_e32 v187, v92, v92
	v_fmac_f32_e32 v187, v93, v93
	v_fmac_f32_e32 v187, v94, v94
	v_fmac_f32_e32 v187, v95, v95
	v_fmac_f32_e32 v187, v96, v96
	v_fmac_f32_e32 v187, v97, v97
	v_fmac_f32_e32 v187, v98, v98
	v_fmac_f32_e32 v187, v99, v99
	v_fmac_f32_e32 v187, v100, v100
	v_fmac_f32_e32 v187, v101, v101
	s_waitcnt vmcnt(4)
	v_mul_f32_e32 v188, v102, v102
	v_fmac_f32_e32 v188, v103, v103
	v_fmac_f32_e32 v188, v104, v104
	v_fmac_f32_e32 v188, v105, v105
	v_fmac_f32_e32 v188, v106, v106
	v_fmac_f32_e32 v188, v107, v107
	v_fmac_f32_e32 v188, v108, v108
	v_fmac_f32_e32 v188, v109, v109
	v_fmac_f32_e32 v188, v110, v110
	v_fmac_f32_e32 v188, v111, v111
	v_fmac_f32_e32 v188, v112, v112
	v_fmac_f32_e32 v188, v113, v113
	v_fmac_f32_e32 v188, v114, v114
	v_fmac_f32_e32 v188, v115, v115
	v_fmac_f32_e32 v188, v116, v116
	v_fmac_f32_e32 v188, v117, v117
	s_waitcnt vmcnt(0)
	v_mul_f32_e32 v189, v118, v118
	v_fmac_f32_e32 v189, v119, v119
	v_fmac_f32_e32 v189, v120, v120
	v_fmac_f32_e32 v189, v121, v121
	v_fmac_f32_e32 v189, v122, v122
	v_fmac_f32_e32 v189, v123, v123
	v_fmac_f32_e32 v189, v124, v124
	v_fmac_f32_e32 v189, v125, v125
	v_fmac_f32_e32 v189, v126, v126
	v_fmac_f32_e32 v189, v127, v127
	v_fmac_f32_e32 v189, v128, v128
	v_fmac_f32_e32 v189, v129, v129
	v_fmac_f32_e32 v189, v130, v130
	v_fmac_f32_e32 v189, v131, v131
	v_fmac_f32_e32 v189, v132, v132
	v_fmac_f32_e32 v189, v133, v133
	s_nop 1
	v_add_f32_dpp v186, v186, v186 row_ror:8 row_mask:0xf bank_mask:0xf
	v_add_f32_dpp v187, v187, v187 row_ror:8 row_mask:0xf bank_mask:0xf
	v_add_f32_dpp v188, v188, v188 row_ror:8 row_mask:0xf bank_mask:0xf
	v_add_f32_dpp v189, v189, v189 row_ror:8 row_mask:0xf bank_mask:0xf
	v_add_f32_dpp v186, v186, v186 row_ror:4 row_mask:0xf bank_mask:0xf
	v_add_f32_dpp v187, v187, v187 row_ror:4 row_mask:0xf bank_mask:0xf
	v_add_f32_dpp v188, v188, v188 row_ror:4 row_mask:0xf bank_mask:0xf
	v_add_f32_dpp v189, v189, v189 row_ror:4 row_mask:0xf bank_mask:0xf
	v_add_f32_dpp v186, v186, v186 row_ror:2 row_mask:0xf bank_mask:0xf
	v_add_f32_dpp v187, v187, v187 row_ror:2 row_mask:0xf bank_mask:0xf
	v_add_f32_dpp v188, v188, v188 row_ror:2 row_mask:0xf bank_mask:0xf
	v_add_f32_dpp v189, v189, v189 row_ror:2 row_mask:0xf bank_mask:0xf
	v_add_f32_dpp v186, v186, v186 row_ror:1 row_mask:0xf bank_mask:0xf
	v_add_f32_dpp v187, v187, v187 row_ror:1 row_mask:0xf bank_mask:0xf
	v_add_f32_dpp v188, v188, v188 row_ror:1 row_mask:0xf bank_mask:0xf
	v_add_f32_dpp v189, v189, v189 row_ror:1 row_mask:0xf bank_mask:0xf
	v_mov_b32_e32 v190, v186
	v_mov_b32_e32 v191, v187
	v_mov_b32_e32 v192, v188
	v_mov_b32_e32 v193, v189
	s_nop 1
	v_permlane16_swap_b32_e32 v190, v186
	v_permlane16_swap_b32_e32 v191, v187
	v_permlane16_swap_b32_e32 v192, v188
	v_permlane16_swap_b32_e32 v193, v189
	v_add_f32_e32 v186, v186, v190
	v_add_f32_e32 v187, v187, v191
	v_add_f32_e32 v188, v188, v192
	v_add_f32_e32 v189, v189, v193
	v_mov_b32_e32 v190, v186
	v_mov_b32_e32 v191, v187
	v_mov_b32_e32 v192, v188
	v_mov_b32_e32 v193, v189
	s_nop 1
	v_permlane32_swap_b32_e32 v190, v186
	v_permlane32_swap_b32_e32 v191, v187
	v_permlane32_swap_b32_e32 v192, v188
	v_permlane32_swap_b32_e32 v193, v189
	v_add_f32_e32 v186, v186, v190
	v_add_f32_e32 v187, v187, v191
	v_add_f32_e32 v188, v188, v192
	v_add_f32_e32 v189, v189, v193
	v_fma_f32 v186, v186, s3, v167
	v_fma_f32 v187, v187, s3, v167
	v_fma_f32 v188, v188, s3, v167
	v_fma_f32 v189, v189, s3, v167
	v_rsq_f32_e32 v186, v186
	v_rsq_f32_e32 v187, v187
	v_rsq_f32_e32 v188, v188
	v_rsq_f32_e32 v189, v189
	s_nop 0
	v_mul_f32_e32 v70, v70, v186
	v_mul_f32_e32 v71, v71, v186
	v_mul_f32_e32 v72, v72, v186
	v_mul_f32_e32 v73, v73, v186
	v_mul_f32_e32 v74, v74, v186
	v_mul_f32_e32 v75, v75, v186
	v_mul_f32_e32 v76, v76, v186
	v_mul_f32_e32 v77, v77, v186
	v_mul_f32_e32 v78, v78, v186
	v_mul_f32_e32 v79, v79, v186
	v_mul_f32_e32 v80, v80, v186
	v_mul_f32_e32 v81, v81, v186
	v_mul_f32_e32 v82, v82, v186
	v_mul_f32_e32 v83, v83, v186
	v_mul_f32_e32 v84, v84, v186
	v_mul_f32_e32 v85, v85, v186
	v_fma_f32 v70, v70, v150, v170
	v_fma_f32 v71, v71, v151, v171
	v_fma_f32 v72, v72, v152, v172
	v_fma_f32 v73, v73, v153, v173
	v_fma_f32 v74, v74, v154, v174
	v_fma_f32 v75, v75, v155, v175
	v_fma_f32 v76, v76, v156, v176
	v_fma_f32 v77, v77, v157, v177
	v_fma_f32 v78, v78, v158, v178
	v_fma_f32 v79, v79, v159, v179
	v_fma_f32 v80, v80, v160, v180
	v_fma_f32 v81, v81, v161, v181
	v_fma_f32 v82, v82, v162, v182
	v_fma_f32 v83, v83, v163, v183
	v_fma_f32 v84, v84, v164, v184
	v_fma_f32 v85, v85, v165, v185
	v_cvt_pk_bf16_f32 v70, v70, v71
	v_cvt_pk_bf16_f32 v71, v72, v73
	v_cvt_pk_bf16_f32 v72, v74, v75
	v_cvt_pk_bf16_f32 v73, v76, v77
	v_cvt_pk_bf16_f32 v78, v78, v79
	v_cvt_pk_bf16_f32 v79, v80, v81
	v_cvt_pk_bf16_f32 v80, v82, v83
	v_cvt_pk_bf16_f32 v81, v84, v85
	ds_write_b128 v202, v[70:73] offset:0
	ds_write_b128 v202, v[78:81] offset:1024
	v_mul_f32_e32 v86, v86, v187
	v_mul_f32_e32 v87, v87, v187
	v_mul_f32_e32 v88, v88, v187
	v_mul_f32_e32 v89, v89, v187
	v_mul_f32_e32 v90, v90, v187
	v_mul_f32_e32 v91, v91, v187
	v_mul_f32_e32 v92, v92, v187
	v_mul_f32_e32 v93, v93, v187
	v_mul_f32_e32 v94, v94, v187
	v_mul_f32_e32 v95, v95, v187
	v_mul_f32_e32 v96, v96, v187
	v_mul_f32_e32 v97, v97, v187
	v_mul_f32_e32 v98, v98, v187
	v_mul_f32_e32 v99, v99, v187
	v_mul_f32_e32 v100, v100, v187
	v_mul_f32_e32 v101, v101, v187
	v_fma_f32 v86, v86, v150, v170
	v_fma_f32 v87, v87, v151, v171
	v_fma_f32 v88, v88, v152, v172
	v_fma_f32 v89, v89, v153, v173
	v_fma_f32 v90, v90, v154, v174
	v_fma_f32 v91, v91, v155, v175
	v_fma_f32 v92, v92, v156, v176
	v_fma_f32 v93, v93, v157, v177
	v_fma_f32 v94, v94, v158, v178
	v_fma_f32 v95, v95, v159, v179
	v_fma_f32 v96, v96, v160, v180
	v_fma_f32 v97, v97, v161, v181
	v_fma_f32 v98, v98, v162, v182
	v_fma_f32 v99, v99, v163, v183
	v_fma_f32 v100, v100, v164, v184
	v_fma_f32 v101, v101, v165, v185
	v_cvt_pk_bf16_f32 v86, v86, v87
	v_cvt_pk_bf16_f32 v87, v88, v89
	v_cvt_pk_bf16_f32 v88, v90, v91
	v_cvt_pk_bf16_f32 v89, v92, v93
	v_cvt_pk_bf16_f32 v94, v94, v95
	v_cvt_pk_bf16_f32 v95, v96, v97
	v_cvt_pk_bf16_f32 v96, v98, v99
	v_cvt_pk_bf16_f32 v97, v100, v101
	ds_write_b128 v202, v[86:89] offset:2048
	ds_write_b128 v202, v[94:97] offset:3072
	v_mul_f32_e32 v102, v102, v188
	v_mul_f32_e32 v103, v103, v188
	v_mul_f32_e32 v104, v104, v188
	v_mul_f32_e32 v105, v105, v188
	v_mul_f32_e32 v106, v106, v188
	v_mul_f32_e32 v107, v107, v188
	v_mul_f32_e32 v108, v108, v188
	v_mul_f32_e32 v109, v109, v188
	v_mul_f32_e32 v110, v110, v188
	v_mul_f32_e32 v111, v111, v188
	v_mul_f32_e32 v112, v112, v188
	v_mul_f32_e32 v113, v113, v188
	v_mul_f32_e32 v114, v114, v188
	v_mul_f32_e32 v115, v115, v188
	v_mul_f32_e32 v116, v116, v188
	v_mul_f32_e32 v117, v117, v188
	v_fma_f32 v102, v102, v150, v170
	v_fma_f32 v103, v103, v151, v171
	v_fma_f32 v104, v104, v152, v172
	v_fma_f32 v105, v105, v153, v173
	v_fma_f32 v106, v106, v154, v174
	v_fma_f32 v107, v107, v155, v175
	v_fma_f32 v108, v108, v156, v176
	v_fma_f32 v109, v109, v157, v177
	v_fma_f32 v110, v110, v158, v178
	v_fma_f32 v111, v111, v159, v179
	v_fma_f32 v112, v112, v160, v180
	v_fma_f32 v113, v113, v161, v181
	v_fma_f32 v114, v114, v162, v182
	v_fma_f32 v115, v115, v163, v183
	v_fma_f32 v116, v116, v164, v184
	v_fma_f32 v117, v117, v165, v185
	v_cvt_pk_bf16_f32 v102, v102, v103
	v_cvt_pk_bf16_f32 v103, v104, v105
	v_cvt_pk_bf16_f32 v104, v106, v107
	v_cvt_pk_bf16_f32 v105, v108, v109
	v_cvt_pk_bf16_f32 v110, v110, v111
	v_cvt_pk_bf16_f32 v111, v112, v113
	v_cvt_pk_bf16_f32 v112, v114, v115
	v_cvt_pk_bf16_f32 v113, v116, v117
	ds_write_b128 v202, v[102:105] offset:4096
	ds_write_b128 v202, v[110:113] offset:5120
	v_mul_f32_e32 v118, v118, v189
	v_mul_f32_e32 v119, v119, v189
	v_mul_f32_e32 v120, v120, v189
	v_mul_f32_e32 v121, v121, v189
	v_mul_f32_e32 v122, v122, v189
	v_mul_f32_e32 v123, v123, v189
	v_mul_f32_e32 v124, v124, v189
	v_mul_f32_e32 v125, v125, v189
	v_mul_f32_e32 v126, v126, v189
	v_mul_f32_e32 v127, v127, v189
	v_mul_f32_e32 v128, v128, v189
	v_mul_f32_e32 v129, v129, v189
	v_mul_f32_e32 v130, v130, v189
	v_mul_f32_e32 v131, v131, v189
	v_mul_f32_e32 v132, v132, v189
	v_mul_f32_e32 v133, v133, v189
	v_fma_f32 v118, v118, v150, v170
	v_fma_f32 v119, v119, v151, v171
	v_fma_f32 v120, v120, v152, v172
	v_fma_f32 v121, v121, v153, v173
	v_fma_f32 v122, v122, v154, v174
	v_fma_f32 v123, v123, v155, v175
	v_fma_f32 v124, v124, v156, v176
	v_fma_f32 v125, v125, v157, v177
	v_fma_f32 v126, v126, v158, v178
	v_fma_f32 v127, v127, v159, v179
	v_fma_f32 v128, v128, v160, v180
	v_fma_f32 v129, v129, v161, v181
	v_fma_f32 v130, v130, v162, v182
	v_fma_f32 v131, v131, v163, v183
	v_fma_f32 v132, v132, v164, v184
	v_fma_f32 v133, v133, v165, v185
	v_cvt_pk_bf16_f32 v118, v118, v119
	v_cvt_pk_bf16_f32 v119, v120, v121
	v_cvt_pk_bf16_f32 v120, v122, v123
	v_cvt_pk_bf16_f32 v121, v124, v125
	v_cvt_pk_bf16_f32 v126, v126, v127
	v_cvt_pk_bf16_f32 v127, v128, v129
	v_cvt_pk_bf16_f32 v128, v130, v131
	v_cvt_pk_bf16_f32 v129, v132, v133
	ds_write_b128 v202, v[118:121] offset:6144
	ds_write_b128 v202, v[126:129] offset:7168
	global_load_dwordx4 v[70:73], v201, s[10:11] offset:0
	global_load_dwordx4 v[74:77], v201, s[10:11] offset:16
	global_load_dwordx4 v[78:81], v201, s[10:11] offset:2048
	global_load_dwordx4 v[82:85], v201, s[10:11] offset:2064
	s_add_u32 s10, s10, 0x1000
	s_addc_u32 s11, s11, 0
	global_load_dwordx4 v[86:89], v201, s[10:11] offset:0
	global_load_dwordx4 v[90:93], v201, s[10:11] offset:16
	global_load_dwordx4 v[94:97], v201, s[10:11] offset:2048
	global_load_dwordx4 v[98:101], v201, s[10:11] offset:2064
	s_add_u32 s10, s10, 0x1000
	s_addc_u32 s11, s11, 0
	global_load_dwordx4 v[102:105], v201, s[10:11] offset:0
	global_load_dwordx4 v[106:109], v201, s[10:11] offset:16
	global_load_dwordx4 v[110:113], v201, s[10:11] offset:2048
	global_load_dwordx4 v[114:117], v201, s[10:11] offset:2064
	s_add_u32 s10, s10, 0x1000
	s_addc_u32 s11, s11, 0
	global_load_dwordx4 v[118:121], v201, s[10:11] offset:0
	global_load_dwordx4 v[122:125], v201, s[10:11] offset:16
	global_load_dwordx4 v[126:129], v201, s[10:11] offset:2048
	global_load_dwordx4 v[130:133], v201, s[10:11] offset:2064
	s_add_u32 s10, s10, 0x1000
	s_addc_u32 s11, s11, 0
	s_waitcnt vmcnt(12)
	v_mul_f32_e32 v186, v70, v70
	v_fmac_f32_e32 v186, v71, v71
	v_fmac_f32_e32 v186, v72, v72
	v_fmac_f32_e32 v186, v73, v73
	v_fmac_f32_e32 v186, v74, v74
	v_fmac_f32_e32 v186, v75, v75
	v_fmac_f32_e32 v186, v76, v76
	v_fmac_f32_e32 v186, v77, v77
	v_fmac_f32_e32 v186, v78, v78
	v_fmac_f32_e32 v186, v79, v79
	v_fmac_f32_e32 v186, v80, v80
	v_fmac_f32_e32 v186, v81, v81
	v_fmac_f32_e32 v186, v82, v82
	v_fmac_f32_e32 v186, v83, v83
	v_fmac_f32_e32 v186, v84, v84
	v_fmac_f32_e32 v186, v85, v85
	s_waitcnt vmcnt(8)
	v_mul_f32_e32 v187, v86, v86
	v_fmac_f32_e32 v187, v87, v87
	v_fmac_f32_e32 v187, v88, v88
	v_fmac_f32_e32 v187, v89, v89
	v_fmac_f32_e32 v187, v90, v90
	v_fmac_f32_e32 v187, v91, v91
	v_fmac_f32_e32 v187, v92, v92
	v_fmac_f32_e32 v187, v93, v93
	v_fmac_f32_e32 v187, v94, v94
	v_fmac_f32_e32 v187, v95, v95
	v_fmac_f32_e32 v187, v96, v96
	v_fmac_f32_e32 v187, v97, v97
	v_fmac_f32_e32 v187, v98, v98
	v_fmac_f32_e32 v187, v99, v99
	v_fmac_f32_e32 v187, v100, v100
	v_fmac_f32_e32 v187, v101, v101
	s_waitcnt vmcnt(4)
	v_mul_f32_e32 v188, v102, v102
	v_fmac_f32_e32 v188, v103, v103
	v_fmac_f32_e32 v188, v104, v104
	v_fmac_f32_e32 v188, v105, v105
	v_fmac_f32_e32 v188, v106, v106
	v_fmac_f32_e32 v188, v107, v107
	v_fmac_f32_e32 v188, v108, v108
	v_fmac_f32_e32 v188, v109, v109
	v_fmac_f32_e32 v188, v110, v110
	v_fmac_f32_e32 v188, v111, v111
	v_fmac_f32_e32 v188, v112, v112
	v_fmac_f32_e32 v188, v113, v113
	v_fmac_f32_e32 v188, v114, v114
	v_fmac_f32_e32 v188, v115, v115
	v_fmac_f32_e32 v188, v116, v116
	v_fmac_f32_e32 v188, v117, v117
	s_waitcnt vmcnt(0)
	v_mul_f32_e32 v189, v118, v118
	v_fmac_f32_e32 v189, v119, v119
	v_fmac_f32_e32 v189, v120, v120
	v_fmac_f32_e32 v189, v121, v121
	v_fmac_f32_e32 v189, v122, v122
	v_fmac_f32_e32 v189, v123, v123
	v_fmac_f32_e32 v189, v124, v124
	v_fmac_f32_e32 v189, v125, v125
	v_fmac_f32_e32 v189, v126, v126
	v_fmac_f32_e32 v189, v127, v127
	v_fmac_f32_e32 v189, v128, v128
	v_fmac_f32_e32 v189, v129, v129
	v_fmac_f32_e32 v189, v130, v130
	v_fmac_f32_e32 v189, v131, v131
	v_fmac_f32_e32 v189, v132, v132
	v_fmac_f32_e32 v189, v133, v133
	s_nop 1
	v_add_f32_dpp v186, v186, v186 row_ror:8 row_mask:0xf bank_mask:0xf
	v_add_f32_dpp v187, v187, v187 row_ror:8 row_mask:0xf bank_mask:0xf
	v_add_f32_dpp v188, v188, v188 row_ror:8 row_mask:0xf bank_mask:0xf
	v_add_f32_dpp v189, v189, v189 row_ror:8 row_mask:0xf bank_mask:0xf
	v_add_f32_dpp v186, v186, v186 row_ror:4 row_mask:0xf bank_mask:0xf
	v_add_f32_dpp v187, v187, v187 row_ror:4 row_mask:0xf bank_mask:0xf
	v_add_f32_dpp v188, v188, v188 row_ror:4 row_mask:0xf bank_mask:0xf
	v_add_f32_dpp v189, v189, v189 row_ror:4 row_mask:0xf bank_mask:0xf
	v_add_f32_dpp v186, v186, v186 row_ror:2 row_mask:0xf bank_mask:0xf
	v_add_f32_dpp v187, v187, v187 row_ror:2 row_mask:0xf bank_mask:0xf
	v_add_f32_dpp v188, v188, v188 row_ror:2 row_mask:0xf bank_mask:0xf
	v_add_f32_dpp v189, v189, v189 row_ror:2 row_mask:0xf bank_mask:0xf
	v_add_f32_dpp v186, v186, v186 row_ror:1 row_mask:0xf bank_mask:0xf
	v_add_f32_dpp v187, v187, v187 row_ror:1 row_mask:0xf bank_mask:0xf
	v_add_f32_dpp v188, v188, v188 row_ror:1 row_mask:0xf bank_mask:0xf
	v_add_f32_dpp v189, v189, v189 row_ror:1 row_mask:0xf bank_mask:0xf
	v_mov_b32_e32 v190, v186
	v_mov_b32_e32 v191, v187
	v_mov_b32_e32 v192, v188
	v_mov_b32_e32 v193, v189
	s_nop 1
	v_permlane16_swap_b32_e32 v190, v186
	v_permlane16_swap_b32_e32 v191, v187
	v_permlane16_swap_b32_e32 v192, v188
	v_permlane16_swap_b32_e32 v193, v189
	v_add_f32_e32 v186, v186, v190
	v_add_f32_e32 v187, v187, v191
	v_add_f32_e32 v188, v188, v192
	v_add_f32_e32 v189, v189, v193
	v_mov_b32_e32 v190, v186
	v_mov_b32_e32 v191, v187
	v_mov_b32_e32 v192, v188
	v_mov_b32_e32 v193, v189
	s_nop 1
	v_permlane32_swap_b32_e32 v190, v186
	v_permlane32_swap_b32_e32 v191, v187
	v_permlane32_swap_b32_e32 v192, v188
	v_permlane32_swap_b32_e32 v193, v189
	v_add_f32_e32 v186, v186, v190
	v_add_f32_e32 v187, v187, v191
	v_add_f32_e32 v188, v188, v192
	v_add_f32_e32 v189, v189, v193
	v_fma_f32 v186, v186, s3, v167
	v_fma_f32 v187, v187, s3, v167
	v_fma_f32 v188, v188, s3, v167
	v_fma_f32 v189, v189, s3, v167
	v_rsq_f32_e32 v186, v186
	v_rsq_f32_e32 v187, v187
	v_rsq_f32_e32 v188, v188
	v_rsq_f32_e32 v189, v189
	s_nop 0
	v_mul_f32_e32 v70, v70, v186
	v_mul_f32_e32 v71, v71, v186
	v_mul_f32_e32 v72, v72, v186
	v_mul_f32_e32 v73, v73, v186
	v_mul_f32_e32 v74, v74, v186
	v_mul_f32_e32 v75, v75, v186
	v_mul_f32_e32 v76, v76, v186
	v_mul_f32_e32 v77, v77, v186
	v_mul_f32_e32 v78, v78, v186
	v_mul_f32_e32 v79, v79, v186
	v_mul_f32_e32 v80, v80, v186
	v_mul_f32_e32 v81, v81, v186
	v_mul_f32_e32 v82, v82, v186
	v_mul_f32_e32 v83, v83, v186
	v_mul_f32_e32 v84, v84, v186
	v_mul_f32_e32 v85, v85, v186
	v_fma_f32 v70, v70, v150, v170
	v_fma_f32 v71, v71, v151, v171
	v_fma_f32 v72, v72, v152, v172
	v_fma_f32 v73, v73, v153, v173
	v_fma_f32 v74, v74, v154, v174
	v_fma_f32 v75, v75, v155, v175
	v_fma_f32 v76, v76, v156, v176
	v_fma_f32 v77, v77, v157, v177
	v_fma_f32 v78, v78, v158, v178
	v_fma_f32 v79, v79, v159, v179
	v_fma_f32 v80, v80, v160, v180
	v_fma_f32 v81, v81, v161, v181
	v_fma_f32 v82, v82, v162, v182
	v_fma_f32 v83, v83, v163, v183
	v_fma_f32 v84, v84, v164, v184
	v_fma_f32 v85, v85, v165, v185
	v_cvt_pk_bf16_f32 v70, v70, v71
	v_cvt_pk_bf16_f32 v71, v72, v73
	v_cvt_pk_bf16_f32 v72, v74, v75
	v_cvt_pk_bf16_f32 v73, v76, v77
	v_cvt_pk_bf16_f32 v78, v78, v79
	v_cvt_pk_bf16_f32 v79, v80, v81
	v_cvt_pk_bf16_f32 v80, v82, v83
	v_cvt_pk_bf16_f32 v81, v84, v85
	ds_write_b128 v202, v[70:73] offset:8192
	ds_write_b128 v202, v[78:81] offset:9216
	v_mul_f32_e32 v86, v86, v187
	v_mul_f32_e32 v87, v87, v187
	v_mul_f32_e32 v88, v88, v187
	v_mul_f32_e32 v89, v89, v187
	v_mul_f32_e32 v90, v90, v187
	v_mul_f32_e32 v91, v91, v187
	v_mul_f32_e32 v92, v92, v187
	v_mul_f32_e32 v93, v93, v187
	v_mul_f32_e32 v94, v94, v187
	v_mul_f32_e32 v95, v95, v187
	v_mul_f32_e32 v96, v96, v187
	v_mul_f32_e32 v97, v97, v187
	v_mul_f32_e32 v98, v98, v187
	v_mul_f32_e32 v99, v99, v187
	v_mul_f32_e32 v100, v100, v187
	v_mul_f32_e32 v101, v101, v187
	v_fma_f32 v86, v86, v150, v170
	v_fma_f32 v87, v87, v151, v171
	v_fma_f32 v88, v88, v152, v172
	v_fma_f32 v89, v89, v153, v173
	v_fma_f32 v90, v90, v154, v174
	v_fma_f32 v91, v91, v155, v175
	v_fma_f32 v92, v92, v156, v176
	v_fma_f32 v93, v93, v157, v177
	v_fma_f32 v94, v94, v158, v178
	v_fma_f32 v95, v95, v159, v179
	v_fma_f32 v96, v96, v160, v180
	v_fma_f32 v97, v97, v161, v181
	v_fma_f32 v98, v98, v162, v182
	v_fma_f32 v99, v99, v163, v183
	v_fma_f32 v100, v100, v164, v184
	v_fma_f32 v101, v101, v165, v185
	v_cvt_pk_bf16_f32 v86, v86, v87
	v_cvt_pk_bf16_f32 v87, v88, v89
	v_cvt_pk_bf16_f32 v88, v90, v91
	v_cvt_pk_bf16_f32 v89, v92, v93
	v_cvt_pk_bf16_f32 v94, v94, v95
	v_cvt_pk_bf16_f32 v95, v96, v97
	v_cvt_pk_bf16_f32 v96, v98, v99
	v_cvt_pk_bf16_f32 v97, v100, v101
	ds_write_b128 v202, v[86:89] offset:10240
	ds_write_b128 v202, v[94:97] offset:11264
	v_mul_f32_e32 v102, v102, v188
	v_mul_f32_e32 v103, v103, v188
	v_mul_f32_e32 v104, v104, v188
	v_mul_f32_e32 v105, v105, v188
	v_mul_f32_e32 v106, v106, v188
	v_mul_f32_e32 v107, v107, v188
	v_mul_f32_e32 v108, v108, v188
	v_mul_f32_e32 v109, v109, v188
	v_mul_f32_e32 v110, v110, v188
	v_mul_f32_e32 v111, v111, v188
	v_mul_f32_e32 v112, v112, v188
	v_mul_f32_e32 v113, v113, v188
	v_mul_f32_e32 v114, v114, v188
	v_mul_f32_e32 v115, v115, v188
	v_mul_f32_e32 v116, v116, v188
	v_mul_f32_e32 v117, v117, v188
	v_fma_f32 v102, v102, v150, v170
	v_fma_f32 v103, v103, v151, v171
	v_fma_f32 v104, v104, v152, v172
	v_fma_f32 v105, v105, v153, v173
	v_fma_f32 v106, v106, v154, v174
	v_fma_f32 v107, v107, v155, v175
	v_fma_f32 v108, v108, v156, v176
	v_fma_f32 v109, v109, v157, v177
	v_fma_f32 v110, v110, v158, v178
	v_fma_f32 v111, v111, v159, v179
	v_fma_f32 v112, v112, v160, v180
	v_fma_f32 v113, v113, v161, v181
	v_fma_f32 v114, v114, v162, v182
	v_fma_f32 v115, v115, v163, v183
	v_fma_f32 v116, v116, v164, v184
	v_fma_f32 v117, v117, v165, v185
	v_cvt_pk_bf16_f32 v102, v102, v103
	v_cvt_pk_bf16_f32 v103, v104, v105
	v_cvt_pk_bf16_f32 v104, v106, v107
	v_cvt_pk_bf16_f32 v105, v108, v109
	v_cvt_pk_bf16_f32 v110, v110, v111
	v_cvt_pk_bf16_f32 v111, v112, v113
	v_cvt_pk_bf16_f32 v112, v114, v115
	v_cvt_pk_bf16_f32 v113, v116, v117
	ds_write_b128 v202, v[102:105] offset:12288
	ds_write_b128 v202, v[110:113] offset:13312
	v_mul_f32_e32 v118, v118, v189
	v_mul_f32_e32 v119, v119, v189
	v_mul_f32_e32 v120, v120, v189
	v_mul_f32_e32 v121, v121, v189
	v_mul_f32_e32 v122, v122, v189
	v_mul_f32_e32 v123, v123, v189
	v_mul_f32_e32 v124, v124, v189
	v_mul_f32_e32 v125, v125, v189
	v_mul_f32_e32 v126, v126, v189
	v_mul_f32_e32 v127, v127, v189
	v_mul_f32_e32 v128, v128, v189
	v_mul_f32_e32 v129, v129, v189
	v_mul_f32_e32 v130, v130, v189
	v_mul_f32_e32 v131, v131, v189
	v_mul_f32_e32 v132, v132, v189
	v_mul_f32_e32 v133, v133, v189
	v_fma_f32 v118, v118, v150, v170
	v_fma_f32 v119, v119, v151, v171
	v_fma_f32 v120, v120, v152, v172
	v_fma_f32 v121, v121, v153, v173
	v_fma_f32 v122, v122, v154, v174
	v_fma_f32 v123, v123, v155, v175
	v_fma_f32 v124, v124, v156, v176
	v_fma_f32 v125, v125, v157, v177
	v_fma_f32 v126, v126, v158, v178
	v_fma_f32 v127, v127, v159, v179
	v_fma_f32 v128, v128, v160, v180
	v_fma_f32 v129, v129, v161, v181
	v_fma_f32 v130, v130, v162, v182
	v_fma_f32 v131, v131, v163, v183
	v_fma_f32 v132, v132, v164, v184
	v_fma_f32 v133, v133, v165, v185
	v_cvt_pk_bf16_f32 v118, v118, v119
	v_cvt_pk_bf16_f32 v119, v120, v121
	v_cvt_pk_bf16_f32 v120, v122, v123
	v_cvt_pk_bf16_f32 v121, v124, v125
	v_cvt_pk_bf16_f32 v126, v126, v127
	v_cvt_pk_bf16_f32 v127, v128, v129
	v_cvt_pk_bf16_f32 v128, v130, v131
	v_cvt_pk_bf16_f32 v129, v132, v133
	ds_write_b128 v202, v[118:121] offset:14336
	ds_write_b128 v202, v[126:129] offset:15360
	s_waitcnt lgkmcnt(0)
	s_barrier
	ds_read2st64_b32 v[10:11], v35 offset1:8
	ds_read2st64_b32 v[12:13], v35 offset0:16 offset1:24
	ds_read2st64_b32 v[14:15], v35 offset0:32 offset1:40
	ds_read2st64_b32 v[16:17], v35 offset0:48 offset1:56
	s_lshl_b32 s8, s7, 6
	s_ashr_i32 s9, s8, 31
	s_waitcnt lgkmcnt(2)
	v_and_b32_e32 v7, 0xffff, v12
	v_and_b32_e32 v6, 0xffff, v10
	v_lshrrev_b32_e32 v10, 16, v10
	v_lshl_or_b32 v6, v11, 16, v6
	v_and_or_b32 v10, v11, s91, v10
	v_lshrrev_b32_e32 v11, 16, v12
	s_lshl_b64 s[8:9], s[8:9], 1
	v_lshl_or_b32 v7, v13, 16, v7
	s_waitcnt lgkmcnt(1)
	v_and_b32_e32 v8, 0xffff, v14
	s_waitcnt lgkmcnt(0)
	v_and_b32_e32 v9, 0xffff, v16
	v_and_or_b32 v11, v13, s91, v11
	v_lshrrev_b32_e32 v12, 16, v14
	v_lshrrev_b32_e32 v13, 16, v16
	v_lshl_add_u64 v[2:3], v[22:23], 0, s[8:9]
	v_lshl_add_u64 v[4:5], v[24:25], 0, s[8:9]
	v_lshl_or_b32 v8, v15, 16, v8
	v_lshl_or_b32 v9, v17, 16, v9
	v_and_or_b32 v12, v15, s91, v12
	v_and_or_b32 v13, v17, s91, v13
	global_store_dwordx4 v[2:3], v[6:9], off
	global_store_dwordx4 v[4:5], v[10:13], off
	ds_read2st64_b32 v[14:15], v35 offset0:64 offset1:72
	ds_read2st64_b32 v[12:13], v35 offset0:80 offset1:88
	ds_read2st64_b32 v[16:17], v35 offset0:96 offset1:104
	ds_read2st64_b32 v[28:29], v35 offset0:112 offset1:120
	s_add_i32 s7, s7, s78
	s_add_i32 s2, s2, s35
	s_waitcnt lgkmcnt(2)
	v_and_b32_e32 v7, 0xffff, v12
	v_lshrrev_b32_e32 v11, 16, v12
	v_and_b32_e32 v6, 0xffff, v14
	v_lshl_or_b32 v7, v13, 16, v7
	s_waitcnt lgkmcnt(1)
	v_and_b32_e32 v8, 0xffff, v16
	s_waitcnt lgkmcnt(0)
	v_and_b32_e32 v9, 0xffff, v28
	v_lshrrev_b32_e32 v10, 16, v14
	v_and_or_b32 v11, v13, s91, v11
	v_lshrrev_b32_e32 v12, 16, v16
	v_lshrrev_b32_e32 v13, 16, v28
	v_lshl_or_b32 v6, v15, 16, v6
	v_lshl_or_b32 v8, v17, 16, v8
	v_lshl_or_b32 v9, v29, 16, v9
	v_and_or_b32 v10, v15, s91, v10
	v_and_or_b32 v12, v17, s91, v12
	v_and_or_b32 v13, v29, s91, v13
	global_store_dwordx4 v[2:3], v[6:9], off offset:16
	global_store_dwordx4 v[4:5], v[10:13], off offset:16
	ds_read2st64_b32 v[14:15], v35 offset0:128 offset1:136
	ds_read2st64_b32 v[12:13], v35 offset0:144 offset1:152
	ds_read2st64_b32 v[16:17], v35 offset0:160 offset1:168
	ds_read2st64_b32 v[28:29], v35 offset0:176 offset1:184
	s_cmpk_gt_i32 s7, 0xbf
	s_waitcnt lgkmcnt(2)
	v_and_b32_e32 v7, 0xffff, v12
	v_lshrrev_b32_e32 v11, 16, v12
	v_and_b32_e32 v6, 0xffff, v14
	v_lshl_or_b32 v7, v13, 16, v7
	s_waitcnt lgkmcnt(1)
	v_and_b32_e32 v8, 0xffff, v16
	s_waitcnt lgkmcnt(0)
	v_and_b32_e32 v9, 0xffff, v28
	v_lshrrev_b32_e32 v10, 16, v14
	v_and_or_b32 v11, v13, s91, v11
	v_lshrrev_b32_e32 v12, 16, v16
	v_lshrrev_b32_e32 v13, 16, v28
	v_lshl_or_b32 v6, v15, 16, v6
	v_lshl_or_b32 v8, v17, 16, v8
	v_lshl_or_b32 v9, v29, 16, v9
	v_and_or_b32 v10, v15, s91, v10
	v_and_or_b32 v12, v17, s91, v12
	v_and_or_b32 v13, v29, s91, v13
	global_store_dwordx4 v[2:3], v[6:9], off offset:32
	global_store_dwordx4 v[4:5], v[10:13], off offset:32
	ds_read2st64_b32 v[14:15], v35 offset0:192 offset1:200
	ds_read2st64_b32 v[12:13], v35 offset0:208 offset1:216
	ds_read2st64_b32 v[16:17], v35 offset0:224 offset1:232
	ds_read2st64_b32 v[28:29], v35 offset0:240 offset1:248
	s_waitcnt lgkmcnt(2)
	v_and_b32_e32 v7, 0xffff, v12
	v_and_b32_e32 v6, 0xffff, v14
	s_waitcnt lgkmcnt(1)
	v_and_b32_e32 v8, 0xffff, v16
	s_waitcnt lgkmcnt(0)
	v_and_b32_e32 v9, 0xffff, v28
	v_lshrrev_b32_e32 v11, 16, v12
	v_lshl_or_b32 v6, v15, 16, v6
	v_lshl_or_b32 v7, v13, 16, v7
	v_lshl_or_b32 v8, v17, 16, v8
	v_lshl_or_b32 v9, v29, 16, v9
	v_lshrrev_b32_e32 v10, 16, v14
	v_and_or_b32 v11, v13, s91, v11
	v_lshrrev_b32_e32 v12, 16, v16
	v_lshrrev_b32_e32 v13, 16, v28
	v_and_or_b32 v10, v15, s91, v10
	v_and_or_b32 v12, v17, s91, v12
	v_and_or_b32 v13, v29, s91, v13
	global_store_dwordx4 v[2:3], v[6:9], off offset:48
	global_store_dwordx4 v[4:5], v[10:13], off offset:48
	ds_read_b32 v10, v36
	ds_read_b32 v11, v37
	ds_read_b32 v12, v38
	ds_read_b32 v13, v39
	ds_read_b32 v14, v40
	ds_read_b32 v15, v41
	ds_read_b32 v16, v42
	ds_read_b32 v17, v43
	s_waitcnt lgkmcnt(7)
	v_and_b32_e32 v6, 0xffff, v10
	v_lshrrev_b32_e32 v10, 16, v10
	s_waitcnt lgkmcnt(6)
	v_lshl_or_b32 v6, v11, 16, v6
	s_waitcnt lgkmcnt(5)
	v_and_b32_e32 v7, 0xffff, v12
	s_waitcnt lgkmcnt(3)
	v_and_b32_e32 v8, 0xffff, v14
	s_waitcnt lgkmcnt(1)
	v_and_b32_e32 v9, 0xffff, v16
	v_and_or_b32 v10, v11, s91, v10
	v_lshrrev_b32_e32 v11, 16, v12
	v_lshl_or_b32 v7, v13, 16, v7
	v_lshl_or_b32 v8, v15, 16, v8
	s_waitcnt lgkmcnt(0)
	v_lshl_or_b32 v9, v17, 16, v9
	v_and_or_b32 v11, v13, s91, v11
	v_lshrrev_b32_e32 v12, 16, v14
	v_lshrrev_b32_e32 v13, 16, v16
	v_and_or_b32 v12, v15, s91, v12
	v_and_or_b32 v13, v17, s91, v13
	global_store_dwordx4 v[2:3], v[6:9], off offset:64
	global_store_dwordx4 v[4:5], v[10:13], off offset:64
	ds_read_b32 v10, v44
	ds_read_b32 v11, v45
	ds_read_b32 v12, v46
	ds_read_b32 v13, v47
	ds_read_b32 v14, v48
	ds_read_b32 v15, v49
	ds_read_b32 v16, v50
	ds_read_b32 v17, v51
	s_waitcnt lgkmcnt(7)
	v_and_b32_e32 v6, 0xffff, v10
	v_lshrrev_b32_e32 v10, 16, v10
	s_waitcnt lgkmcnt(6)
	v_lshl_or_b32 v6, v11, 16, v6
	s_waitcnt lgkmcnt(5)
	v_and_b32_e32 v7, 0xffff, v12
	s_waitcnt lgkmcnt(3)
	v_and_b32_e32 v8, 0xffff, v14
	s_waitcnt lgkmcnt(1)
	v_and_b32_e32 v9, 0xffff, v16
	v_and_or_b32 v10, v11, s91, v10
	v_lshrrev_b32_e32 v11, 16, v12
	v_lshl_or_b32 v7, v13, 16, v7
	v_lshl_or_b32 v8, v15, 16, v8
	s_waitcnt lgkmcnt(0)
	v_lshl_or_b32 v9, v17, 16, v9
	v_and_or_b32 v11, v13, s91, v11
	v_lshrrev_b32_e32 v12, 16, v14
	v_lshrrev_b32_e32 v13, 16, v16
	v_and_or_b32 v12, v15, s91, v12
	v_and_or_b32 v13, v17, s91, v13
	global_store_dwordx4 v[2:3], v[6:9], off offset:80
	global_store_dwordx4 v[4:5], v[10:13], off offset:80
	ds_read_b32 v10, v52
	ds_read_b32 v11, v53
	ds_read_b32 v12, v54
	ds_read_b32 v13, v55
	ds_read_b32 v14, v56
	ds_read_b32 v15, v57
	ds_read_b32 v16, v58
	ds_read_b32 v17, v59
	s_waitcnt lgkmcnt(7)
	v_and_b32_e32 v6, 0xffff, v10
	v_lshrrev_b32_e32 v10, 16, v10
	s_waitcnt lgkmcnt(6)
	v_lshl_or_b32 v6, v11, 16, v6
	s_waitcnt lgkmcnt(5)
	v_and_b32_e32 v7, 0xffff, v12
	s_waitcnt lgkmcnt(3)
	v_and_b32_e32 v8, 0xffff, v14
	s_waitcnt lgkmcnt(1)
	v_and_b32_e32 v9, 0xffff, v16
	v_and_or_b32 v10, v11, s91, v10
	v_lshrrev_b32_e32 v11, 16, v12
	v_lshl_or_b32 v7, v13, 16, v7
	v_lshl_or_b32 v8, v15, 16, v8
	s_waitcnt lgkmcnt(0)
	v_lshl_or_b32 v9, v17, 16, v9
	v_and_or_b32 v11, v13, s91, v11
	v_lshrrev_b32_e32 v12, 16, v14
	v_lshrrev_b32_e32 v13, 16, v16
	v_and_or_b32 v12, v15, s91, v12
	v_and_or_b32 v13, v17, s91, v13
	global_store_dwordx4 v[2:3], v[6:9], off offset:96
	global_store_dwordx4 v[4:5], v[10:13], off offset:96
	ds_read_b32 v10, v60
	ds_read_b32 v11, v61
	ds_read_b32 v12, v62
	ds_read_b32 v13, v63
	ds_read_b32 v14, v64
	ds_read_b32 v15, v65
	ds_read_b32 v16, v66
	ds_read_b32 v17, v67
	s_waitcnt lgkmcnt(7)
	v_and_b32_e32 v6, 0xffff, v10
	v_lshrrev_b32_e32 v10, 16, v10
	s_waitcnt lgkmcnt(6)
	v_lshl_or_b32 v6, v11, 16, v6
	s_waitcnt lgkmcnt(5)
	v_and_b32_e32 v7, 0xffff, v12
	s_waitcnt lgkmcnt(3)
	v_and_b32_e32 v8, 0xffff, v14
	s_waitcnt lgkmcnt(1)
	v_and_b32_e32 v9, 0xffff, v16
	v_and_or_b32 v10, v11, s91, v10
	v_lshrrev_b32_e32 v11, 16, v12
	v_lshl_or_b32 v7, v13, 16, v7
	v_lshl_or_b32 v8, v15, 16, v8
	s_waitcnt lgkmcnt(0)
	v_lshl_or_b32 v9, v17, 16, v9
	v_and_or_b32 v11, v13, s91, v11
	v_lshrrev_b32_e32 v12, 16, v14
	v_lshrrev_b32_e32 v13, 16, v16
	v_and_or_b32 v12, v15, s91, v12
	v_and_or_b32 v13, v17, s91, v13
	global_store_dwordx4 v[2:3], v[6:9], off offset:112
	global_store_dwordx4 v[4:5], v[10:13], off offset:112
	s_barrier
	s_cbranch_scc0 .LBB0_896
